# v044 + softmax row-max trees rewritten as two v_max3 chains (16 ops instead of 53) in attention-A loops
# speedup vs baseline: 1.0090x; 1.0090x over previous
; #define LAS __attribute__((address_space(3)))
; __device__ __forceinline__ int crow(int r, int hi) { return (r & 3) + 8 * (r >> 2) + 4 * hi; }
;     ...
;     auto QK = [&](const LAS unsigned char* sbase, f32x16& s0, f32x16& s1) {
;         const LAS unsigned char* kb = sbase + r32 * KSTR; const int kc0 = (koff >> 3) + hi;
; #pragma unroll
;         for (int r = 0; r < 16; ++r) { s0[r] = 0.f; s1[r] = 0.f; }
; #pragma unroll
;         for (int kh = 0; kh < NKS; kh += 4) {
;             bf16x8 ka[4][2];
; #pragma unroll
;             for (int ks = 0; ks < 4; ++ks) { const int ko = ((kc0 + 2 * (kh + ks)) ^ ksw) << 4; ka[ks][0] = *(const LAS bf16x8*)(kb + ko); ka[ks][1] = *(const LAS bf16x8*)(kb + 32 * KSTR + ko); }
;             __builtin_amdgcn_s_setprio(1);
; #pragma unroll
;             for (int ks = 0; ks < 4; ++ks) { s0 = __builtin_amdgcn_mfma_f32_32x32x16_bf16(ka[ks][0], qf[kh + ks], s0, 0, 0, 0); s1 = __builtin_amdgcn_mfma_f32_32x32x16_bf16(ka[ks][1], qf[kh + ks], s1, 0, 0, 0); }
;             __builtin_amdgcn_s_setprio(0);
;         }
;     };
;     auto SM = [&](unsigned w0, unsigned w1, f32x16& s0, f32x16& s1, bf16x8 (&pb)[2][2]) {
;         if (LAYER == 1) {
; #pragma unroll
;             for (int r = 0; r < 16; ++r) { const int kv = crow(r, hi); if (!((w0 >> kv) & 1u)) s0[r] = -1e30f; if (!((w1 >> kv) & 1u)) s1[r] = -1e30f; } }
;         float mx = fmaxf(s0[0], s1[0]);
; #pragma unroll
;         for (int r = 1; r < 16; ++r) mx = fmaxf(mx, fmaxf(s0[r], s1[r]));
;         mx = fmaxf(mx, __shfl_xor(mx, 32));
;         const bool need = mx > mrun + 8.f;
;         if (__any(need)) { const float mnew = need ? mx : mrun, alpha = __builtin_amdgcn_exp2f(mrun - mnew); mrun = mnew; lrun *= alpha;
; #pragma unroll
;             for (int d = 0; d < 4; ++d)
; #pragma unroll
;                 for (int r = 0; r < 16; ++r) o[d][r] *= alpha; }
;     ...
;             if (work) { QK(sbase, s0, s1); unsigned w0 = 0xffffffffu, w1 = 0xffffffffu; if (LAYER == 1) { const v2u mw = gld<v2u>(mbase, moff + 8u * t); w0 = mw.x; w1 = mw.y; } SM(w0, w1, s0, s1, pb); }
.LBB0_518:
	s_and_b32 s2, s10, 0x10000
	s_add_i32 s48, s51, s2
	s_cmpk_lt_u32 s58, 0x41
	s_cselect_b64 s[42:43], -1, 0
	s_cmp_gt_u32 s58, 64
	s_cbranch_scc1 .LBB0_522
	v_add_u32_e32 v2, s48, v170
	v_add_u32_e32 v72, v2, v171
	v_add_u32_e32 v76, v2, v172
	ds_read_b128 v[68:71], v72
	ds_read_b128 v[72:75], v72 offset:8192
	ds_read_b128 v[176:179], v76
	ds_read_b128 v[180:183], v76 offset:8192
	v_add_u32_e32 v76, v2, v173
	v_add_u32_e32 v2, v2, v174
	ds_read_b128 v[186:189], v76
	ds_read_b128 v[190:193], v76 offset:8192
	ds_read_b128 v[194:197], v2
	ds_read_b128 v[198:201], v2 offset:8192
	s_setprio 1
	s_waitcnt lgkmcnt(7)
	v_mfma_f32_32x32x16_bf16 v[84:99], v[68:71], v[100:103], 0
	s_waitcnt lgkmcnt(6)
	v_mfma_f32_32x32x16_bf16 v[68:83], v[72:75], v[100:103], 0
	s_waitcnt lgkmcnt(5)
	v_mfma_f32_32x32x16_bf16 v[84:99], v[176:179], v[104:107], v[84:99]
	s_waitcnt lgkmcnt(4)
	v_mfma_f32_32x32x16_bf16 v[68:83], v[180:183], v[104:107], v[68:83]
	s_waitcnt lgkmcnt(3)
	v_mfma_f32_32x32x16_bf16 v[84:99], v[186:189], v[108:111], v[84:99]
	s_waitcnt lgkmcnt(2)
	v_mfma_f32_32x32x16_bf16 v[68:83], v[190:193], v[108:111], v[68:83]
	s_waitcnt lgkmcnt(1)
	v_mfma_f32_32x32x16_bf16 v[84:99], v[194:197], v[112:115], v[84:99]
	s_waitcnt lgkmcnt(0)
	v_mfma_f32_32x32x16_bf16 v[68:83], v[198:201], v[112:115], v[68:83]
	s_setprio 0
	s_nop 10
	v_max3_f32 v175, v69, v85, v70
	v_max3_f32 v176, v76, v92, v77
	v_max3_f32 v175, v175, v86, v71
	v_max3_f32 v176, v176, v93, v78
	v_max3_f32 v175, v175, v87, v84
	v_max3_f32 v176, v176, v94, v79
	v_max3_f32 v175, v175, v68, v72
	v_max3_f32 v176, v176, v95, v80
	v_max3_f32 v175, v175, v88, v73
	v_max3_f32 v176, v176, v96, v81
	v_max3_f32 v175, v175, v89, v74
	v_max3_f32 v176, v176, v97, v82
	v_max3_f32 v175, v175, v90, v75
	v_max3_f32 v176, v176, v98, v83
	v_max3_f32 v175, v175, v176, v91
	v_max_f32_e32 v2, v99, v175
	v_and_b32_e32 v176, 64, v184
	v_xor_b32_e32 v175, 32, v184
	v_add_u32_e32 v176, 64, v176
	v_cmp_lt_i32_e32 vcc, v175, v176
	s_nop 1
	v_cndmask_b32_e32 v175, v184, v175, vcc
	v_lshlrev_b32_e32 v175, 2, v175
	ds_bpermute_b32 v175, v175, v2
	s_waitcnt lgkmcnt(0)
	v_max_f32_e32 v175, v175, v175
	v_max_f32_e32 v2, v2, v175
	v_add_f32_e32 v175, 0x41000000, v152
	v_cmp_gt_f32_e32 vcc, v2, v175
	s_cbranch_vccz .LBB0_521
	s_nop 0
	v_cndmask_b32_e32 v175, v152, v2, vcc
	v_sub_f32_e32 v2, v152, v175
	v_exp_f32_e32 v2, v2
	v_mov_b32_e32 v152, v175
	v_mul_f32_e32 v149, v149, v2
	v_pk_mul_f32 v[66:67], v[66:67], v[2:3] op_sel_hi:[1,0]
	v_pk_mul_f32 v[64:65], v[64:65], v[2:3] op_sel_hi:[1,0]
	v_pk_mul_f32 v[62:63], v[62:63], v[2:3] op_sel_hi:[1,0]
	v_pk_mul_f32 v[60:61], v[60:61], v[2:3] op_sel_hi:[1,0]
	v_pk_mul_f32 v[58:59], v[58:59], v[2:3] op_sel_hi:[1,0]
	v_pk_mul_f32 v[56:57], v[56:57], v[2:3] op_sel_hi:[1,0]
	v_pk_mul_f32 v[54:55], v[54:55], v[2:3] op_sel_hi:[1,0]
	v_pk_mul_f32 v[52:53], v[52:53], v[2:3] op_sel_hi:[1,0]
	v_pk_mul_f32 v[50:51], v[50:51], v[2:3] op_sel_hi:[1,0]
	v_pk_mul_f32 v[48:49], v[48:49], v[2:3] op_sel_hi:[1,0]
	v_pk_mul_f32 v[46:47], v[46:47], v[2:3] op_sel_hi:[1,0]
	v_pk_mul_f32 v[44:45], v[44:45], v[2:3] op_sel_hi:[1,0]
	v_pk_mul_f32 v[42:43], v[42:43], v[2:3] op_sel_hi:[1,0]
	v_pk_mul_f32 v[40:41], v[40:41], v[2:3] op_sel_hi:[1,0]
	v_pk_mul_f32 v[38:39], v[38:39], v[2:3] op_sel_hi:[1,0]
	v_pk_mul_f32 v[36:37], v[36:37], v[2:3] op_sel_hi:[1,0]
	v_pk_mul_f32 v[34:35], v[34:35], v[2:3] op_sel_hi:[1,0]
	v_pk_mul_f32 v[32:33], v[32:33], v[2:3] op_sel_hi:[1,0]
	v_pk_mul_f32 v[30:31], v[30:31], v[2:3] op_sel_hi:[1,0]
	v_pk_mul_f32 v[28:29], v[28:29], v[2:3] op_sel_hi:[1,0]
	v_pk_mul_f32 v[26:27], v[26:27], v[2:3] op_sel_hi:[1,0]
	v_pk_mul_f32 v[24:25], v[24:25], v[2:3] op_sel_hi:[1,0]
	v_pk_mul_f32 v[22:23], v[22:23], v[2:3] op_sel_hi:[1,0]
	v_pk_mul_f32 v[20:21], v[20:21], v[2:3] op_sel_hi:[1,0]
	v_pk_mul_f32 v[18:19], v[18:19], v[2:3] op_sel_hi:[1,0]
	v_pk_mul_f32 v[16:17], v[16:17], v[2:3] op_sel_hi:[1,0]
	v_pk_mul_f32 v[14:15], v[14:15], v[2:3] op_sel_hi:[1,0]
	v_pk_mul_f32 v[12:13], v[12:13], v[2:3] op_sel_hi:[1,0]
	v_pk_mul_f32 v[10:11], v[10:11], v[2:3] op_sel_hi:[1,0]
	v_pk_mul_f32 v[8:9], v[8:9], v[2:3] op_sel_hi:[1,0]
	v_pk_mul_f32 v[6:7], v[6:7], v[2:3] op_sel_hi:[1,0]
	v_pk_mul_f32 v[4:5], v[4:5], v[2:3] op_sel_hi:[1,0]

; #define ATT_VREAD(dst, q_) do { const LAS char* vp_ = (const LAS char*)vb + (((q_) >> 1) * 32 + 16 * ((q_) & 1)) * VSTR; \
;         _Pragma("unroll") for (int d_ = 0; d_ < 4; ++d_) { dst[d_][0] = vtr(vp_ + voff[d_][0]); dst[d_][1] = vtr(vp_ + 8 * VSTR + voff[d_][1]); } } while (0)
;     ...
;         float mx = fmaxf(s0[0], s1[0]);
; #pragma unroll
;         for (int r = 1; r < 16; ++r) mx = fmaxf(mx, fmaxf(s0[r], s1[r]));
;         mx = fmaxf(mx, __shfl_xor(mx, 32));
;         const bool need = mx > mrun + 8.f;
;         if (__any(need)) { const float mnew = need ? mx : mrun, alpha = __builtin_amdgcn_exp2f(mrun - mnew); mrun = mnew; lrun *= alpha;
; #pragma unroll
;             for (int d = 0; d < 4; ++d)
; #pragma unroll
;                 for (int r = 0; r < 16; ++r) o[d][r] *= alpha; }
;     ...
;             if (wka) { vb = sa + KBUF + vlane; ATT_VREAD(vpre, 0); SM(wa0, wa1, a0, a1, pba);
.LBB0_586:
	v_add_u32_e32 v148, s1, v194
	s_andn2_b64 vcc, exec, s[28:29]
	v_add_u32_e32 v200, v148, v186
	v_add_u32_e32 v201, v148, v187
	v_add_u32_e32 v202, v148, v188
	v_add_u32_e32 v203, v148, v189
	v_add_u32_e32 v204, v148, v190
	v_add_u32_e32 v205, v148, v191
	v_add_u32_e32 v206, v148, v192
	v_add_u32_e32 v207, v148, v193
	s_cbranch_vccnz .LBB0_590
	v_max3_f32 v156, v101, v69, v102
	v_max3_f32 v157, v108, v76, v109
	v_max3_f32 v156, v156, v70, v103
	v_max3_f32 v157, v157, v77, v110
	v_max3_f32 v156, v156, v71, v68
	v_max3_f32 v157, v157, v78, v111
	v_max3_f32 v156, v156, v100, v104
	v_max3_f32 v157, v157, v79, v112
	v_max3_f32 v156, v156, v72, v105
	v_max3_f32 v157, v157, v80, v113
	v_max3_f32 v156, v156, v73, v106
	v_max3_f32 v157, v157, v81, v114
	v_max3_f32 v156, v156, v74, v107
	v_max3_f32 v157, v157, v82, v115
	v_max3_f32 v156, v156, v157, v75
	v_max_f32_e32 v208, v83, v156
	s_waitcnt vmcnt(0)
	ds_read_b64_tr_b16 v[152:153], v200 offset:16384
	ds_read_b64_tr_b16 v[154:155], v201 offset:18432
	ds_read_b64_tr_b16 v[148:149], v202 offset:16384
	ds_read_b64_tr_b16 v[150:151], v203 offset:18432
	v_mov_b32_e32 v246, v208
	v_mov_b32_e32 v247, v208
	ds_read_b64_tr_b16 v[160:161], v204 offset:16384
	ds_read_b64_tr_b16 v[162:163], v205 offset:18432
	ds_read_b64_tr_b16 v[156:157], v206 offset:16384
	ds_read_b64_tr_b16 v[158:159], v207 offset:18432
	v_permlane32_swap_b32_e32 v246, v247
	v_max3_f32 v208, v208, v246, v247
	v_add_f32_e32 v209, 0x41000000, v170
	v_cmp_gt_f32_e32 vcc, v208, v209
	s_cbranch_vccz .LBB0_589
	s_nop 0
	v_cndmask_b32_e32 v208, v170, v208, vcc
	v_sub_f32_e32 v170, v170, v208
	v_exp_f32_e32 v170, v170
	s_nop 0
	v_mul_f32_e32 v167, v167, v170
	v_pk_mul_f32 v[66:67], v[66:67], v[170:171] op_sel_hi:[1,0]
	v_pk_mul_f32 v[64:65], v[64:65], v[170:171] op_sel_hi:[1,0]
	v_pk_mul_f32 v[62:63], v[62:63], v[170:171] op_sel_hi:[1,0]
	v_pk_mul_f32 v[60:61], v[60:61], v[170:171] op_sel_hi:[1,0]
	v_pk_mul_f32 v[58:59], v[58:59], v[170:171] op_sel_hi:[1,0]
	v_pk_mul_f32 v[56:57], v[56:57], v[170:171] op_sel_hi:[1,0]
	v_pk_mul_f32 v[54:55], v[54:55], v[170:171] op_sel_hi:[1,0]
	v_pk_mul_f32 v[52:53], v[52:53], v[170:171] op_sel_hi:[1,0]
	v_pk_mul_f32 v[50:51], v[50:51], v[170:171] op_sel_hi:[1,0]
	v_pk_mul_f32 v[48:49], v[48:49], v[170:171] op_sel_hi:[1,0]
	v_pk_mul_f32 v[46:47], v[46:47], v[170:171] op_sel_hi:[1,0]
	v_pk_mul_f32 v[44:45], v[44:45], v[170:171] op_sel_hi:[1,0]
	v_pk_mul_f32 v[42:43], v[42:43], v[170:171] op_sel_hi:[1,0]
	v_pk_mul_f32 v[40:41], v[40:41], v[170:171] op_sel_hi:[1,0]
	v_pk_mul_f32 v[38:39], v[38:39], v[170:171] op_sel_hi:[1,0]
	v_pk_mul_f32 v[36:37], v[36:37], v[170:171] op_sel_hi:[1,0]
	v_pk_mul_f32 v[34:35], v[34:35], v[170:171] op_sel_hi:[1,0]
	v_pk_mul_f32 v[32:33], v[32:33], v[170:171] op_sel_hi:[1,0]
	v_pk_mul_f32 v[30:31], v[30:31], v[170:171] op_sel_hi:[1,0]
	v_pk_mul_f32 v[28:29], v[28:29], v[170:171] op_sel_hi:[1,0]
	v_pk_mul_f32 v[26:27], v[26:27], v[170:171] op_sel_hi:[1,0]
	v_pk_mul_f32 v[24:25], v[24:25], v[170:171] op_sel_hi:[1,0]
	v_pk_mul_f32 v[22:23], v[22:23], v[170:171] op_sel_hi:[1,0]
	v_pk_mul_f32 v[20:21], v[20:21], v[170:171] op_sel_hi:[1,0]
	v_pk_mul_f32 v[18:19], v[18:19], v[170:171] op_sel_hi:[1,0]
	v_pk_mul_f32 v[16:17], v[16:17], v[170:171] op_sel_hi:[1,0]
	v_pk_mul_f32 v[14:15], v[14:15], v[170:171] op_sel_hi:[1,0]
	v_pk_mul_f32 v[12:13], v[12:13], v[170:171] op_sel_hi:[1,0]
	v_pk_mul_f32 v[10:11], v[10:11], v[170:171] op_sel_hi:[1,0]
	v_pk_mul_f32 v[8:9], v[8:9], v[170:171] op_sel_hi:[1,0]
	v_pk_mul_f32 v[6:7], v[6:7], v[170:171] op_sel_hi:[1,0]
	v_pk_mul_f32 v[4:5], v[4:5], v[170:171] op_sel_hi:[1,0]
	v_mov_b32_e32 v170, v208

; #define ATT_VREAD(dst, q_) do { const LAS char* vp_ = (const LAS char*)vb + (((q_) >> 1) * 32 + 16 * ((q_) & 1)) * VSTR; \
;         _Pragma("unroll") for (int d_ = 0; d_ < 4; ++d_) { dst[d_][0] = vtr(vp_ + voff[d_][0]); dst[d_][1] = vtr(vp_ + 8 * VSTR + voff[d_][1]); } } while (0)
;     ...
;         float mx = fmaxf(s0[0], s1[0]);
; #pragma unroll
;         for (int r = 1; r < 16; ++r) mx = fmaxf(mx, fmaxf(s0[r], s1[r]));
;         mx = fmaxf(mx, __shfl_xor(mx, 32));
;         const bool need = mx > mrun + 8.f;
;         if (__any(need)) { const float mnew = need ? mx : mrun, alpha = __builtin_amdgcn_exp2f(mrun - mnew); mrun = mnew; lrun *= alpha;
; #pragma unroll
;             for (int d = 0; d < 4; ++d)
; #pragma unroll
;                 for (int r = 0; r < 16; ++r) o[d][r] *= alpha; }
;     ...
;             if (wkb) { vb = sbb + KBUF + vlane; ATT_VREAD(vpre, 0); SM(wb0, wb1, b0, b1, pbb);
.LBB0_590:
	s_and_b64 vcc, exec, s[2:3]
	s_cbranch_vccnz .LBB0_594
	v_max3_f32 v156, v117, v85, v118
	v_max3_f32 v157, v124, v92, v125
	v_max3_f32 v156, v156, v86, v119
	v_max3_f32 v157, v157, v93, v126
	v_max3_f32 v156, v156, v87, v84
	v_max3_f32 v157, v157, v94, v127
	v_max3_f32 v156, v156, v116, v120
	v_max3_f32 v157, v157, v95, v128
	v_max3_f32 v156, v156, v88, v121
	v_max3_f32 v157, v157, v96, v129
	v_max3_f32 v156, v156, v89, v122
	v_max3_f32 v157, v157, v97, v130
	v_max3_f32 v156, v156, v90, v123
	v_max3_f32 v157, v157, v98, v131
	v_max3_f32 v156, v156, v157, v91
	v_max_f32_e32 v208, v99, v156
	s_waitcnt vmcnt(0)
	ds_read_b64_tr_b16 v[152:153], v200 offset:49152
	ds_read_b64_tr_b16 v[154:155], v201 offset:51200
	ds_read_b64_tr_b16 v[148:149], v202 offset:49152
	ds_read_b64_tr_b16 v[150:151], v203 offset:51200
	v_mov_b32_e32 v246, v208
	v_mov_b32_e32 v247, v208
	ds_read_b64_tr_b16 v[160:161], v204 offset:49152
	ds_read_b64_tr_b16 v[162:163], v205 offset:51200
	ds_read_b64_tr_b16 v[156:157], v206 offset:49152
	ds_read_b64_tr_b16 v[158:159], v207 offset:51200
	v_permlane32_swap_b32_e32 v246, v247
	v_max3_f32 v208, v208, v246, v247
	v_add_f32_e32 v209, 0x41000000, v170
	v_cmp_gt_f32_e32 vcc, v208, v209
	s_cbranch_vccz .LBB0_593
	s_nop 0
	v_cndmask_b32_e32 v208, v170, v208, vcc
	v_sub_f32_e32 v170, v170, v208
	v_exp_f32_e32 v170, v170
	s_nop 0
	v_mul_f32_e32 v167, v167, v170
	v_pk_mul_f32 v[66:67], v[66:67], v[170:171] op_sel_hi:[1,0]
	v_pk_mul_f32 v[64:65], v[64:65], v[170:171] op_sel_hi:[1,0]
	v_pk_mul_f32 v[62:63], v[62:63], v[170:171] op_sel_hi:[1,0]
	v_pk_mul_f32 v[60:61], v[60:61], v[170:171] op_sel_hi:[1,0]
	v_pk_mul_f32 v[58:59], v[58:59], v[170:171] op_sel_hi:[1,0]
	v_pk_mul_f32 v[56:57], v[56:57], v[170:171] op_sel_hi:[1,0]
	v_pk_mul_f32 v[54:55], v[54:55], v[170:171] op_sel_hi:[1,0]
	v_pk_mul_f32 v[52:53], v[52:53], v[170:171] op_sel_hi:[1,0]
	v_pk_mul_f32 v[50:51], v[50:51], v[170:171] op_sel_hi:[1,0]
	v_pk_mul_f32 v[48:49], v[48:49], v[170:171] op_sel_hi:[1,0]
	v_pk_mul_f32 v[46:47], v[46:47], v[170:171] op_sel_hi:[1,0]
	v_pk_mul_f32 v[44:45], v[44:45], v[170:171] op_sel_hi:[1,0]
	v_pk_mul_f32 v[42:43], v[42:43], v[170:171] op_sel_hi:[1,0]
	v_pk_mul_f32 v[40:41], v[40:41], v[170:171] op_sel_hi:[1,0]
	v_pk_mul_f32 v[38:39], v[38:39], v[170:171] op_sel_hi:[1,0]
	v_pk_mul_f32 v[36:37], v[36:37], v[170:171] op_sel_hi:[1,0]
	v_pk_mul_f32 v[34:35], v[34:35], v[170:171] op_sel_hi:[1,0]
	v_pk_mul_f32 v[32:33], v[32:33], v[170:171] op_sel_hi:[1,0]
	v_pk_mul_f32 v[30:31], v[30:31], v[170:171] op_sel_hi:[1,0]
	v_pk_mul_f32 v[28:29], v[28:29], v[170:171] op_sel_hi:[1,0]
	v_pk_mul_f32 v[26:27], v[26:27], v[170:171] op_sel_hi:[1,0]
	v_pk_mul_f32 v[24:25], v[24:25], v[170:171] op_sel_hi:[1,0]
	v_pk_mul_f32 v[22:23], v[22:23], v[170:171] op_sel_hi:[1,0]
	v_pk_mul_f32 v[20:21], v[20:21], v[170:171] op_sel_hi:[1,0]
	v_pk_mul_f32 v[18:19], v[18:19], v[170:171] op_sel_hi:[1,0]
	v_pk_mul_f32 v[16:17], v[16:17], v[170:171] op_sel_hi:[1,0]
	v_pk_mul_f32 v[14:15], v[14:15], v[170:171] op_sel_hi:[1,0]
	v_pk_mul_f32 v[12:13], v[12:13], v[170:171] op_sel_hi:[1,0]
	v_pk_mul_f32 v[10:11], v[10:11], v[170:171] op_sel_hi:[1,0]
	v_pk_mul_f32 v[8:9], v[8:9], v[170:171] op_sel_hi:[1,0]
	v_pk_mul_f32 v[6:7], v[6:7], v[170:171] op_sel_hi:[1,0]
	v_pk_mul_f32 v[4:5], v[4:5], v[170:171] op_sel_hi:[1,0]
	v_mov_b32_e32 v170, v208

; #define ATT_VREAD(dst, q_) do { const LAS char* vp_ = (const LAS char*)vb + (((q_) >> 1) * 32 + 16 * ((q_) & 1)) * VSTR; \
;         _Pragma("unroll") for (int d_ = 0; d_ < 4; ++d_) { dst[d_][0] = vtr(vp_ + voff[d_][0]); dst[d_][1] = vtr(vp_ + 8 * VSTR + voff[d_][1]); } } while (0)
;     ...
;         float mx = fmaxf(s0[0], s1[0]);
; #pragma unroll
;         for (int r = 1; r < 16; ++r) mx = fmaxf(mx, fmaxf(s0[r], s1[r]));
;         mx = fmaxf(mx, __shfl_xor(mx, 32));
;         const bool need = mx > mrun + 8.f;
;         if (__any(need)) { const float mnew = need ? mx : mrun, alpha = __builtin_amdgcn_exp2f(mrun - mnew); mrun = mnew; lrun *= alpha;
; #pragma unroll
;             for (int d = 0; d < 4; ++d)
; #pragma unroll
;                 for (int r = 0; r < 16; ++r) o[d][r] *= alpha; }
;     ...
;             if (wka) { vb = sa + KBUF + vlane; ATT_VREAD(vpre, 0); SM(wa0, wa1, a0, a1, pba);
.LBB0_3320:
	v_add_u32_e32 v146, s45, v195
	s_and_b64 vcc, exec, s[4:5]
	v_add_u32_e32 v201, v146, v171
	v_add_u32_e32 v202, v146, v188
	v_add_u32_e32 v203, v146, v189
	v_add_u32_e32 v204, v146, v190
	v_add_u32_e32 v205, v146, v191
	v_add_u32_e32 v206, v146, v192
	v_add_u32_e32 v207, v146, v193
	v_add_u32_e32 v208, v146, v194
	s_cbranch_vccnz .LBB0_3324
	v_max3_f32 v154, v99, v67, v100
	v_max3_f32 v155, v106, v74, v107
	v_max3_f32 v154, v154, v68, v101
	v_max3_f32 v155, v155, v75, v108
	v_max3_f32 v154, v154, v69, v66
	v_max3_f32 v155, v155, v76, v109
	v_max3_f32 v154, v154, v98, v102
	v_max3_f32 v155, v155, v77, v110
	v_max3_f32 v154, v154, v70, v103
	v_max3_f32 v155, v155, v78, v111
	v_max3_f32 v154, v154, v71, v104
	v_max3_f32 v155, v155, v79, v112
	v_max3_f32 v154, v154, v72, v105
	v_max3_f32 v155, v155, v80, v113
	v_max3_f32 v154, v154, v155, v73
	v_max_f32_e32 v209, v81, v154
	s_waitcnt vmcnt(0)
	ds_read_b64_tr_b16 v[150:151], v201 offset:16384
	ds_read_b64_tr_b16 v[152:153], v202 offset:18432
	ds_read_b64_tr_b16 v[146:147], v203 offset:16384
	ds_read_b64_tr_b16 v[148:149], v204 offset:18432
	v_mov_b32_e32 v246, v209
	v_mov_b32_e32 v247, v209
	ds_read_b64_tr_b16 v[158:159], v205 offset:16384
	ds_read_b64_tr_b16 v[160:161], v206 offset:18432
	ds_read_b64_tr_b16 v[154:155], v207 offset:16384
	ds_read_b64_tr_b16 v[156:157], v208 offset:18432
	v_permlane32_swap_b32_e32 v246, v247
	v_max3_f32 v209, v209, v246, v247
	v_add_f32_e32 v210, 0x41000000, v170
	v_cmp_gt_f32_e32 vcc, v209, v210
	s_cbranch_vccz .LBB0_3323
	s_nop 0
	v_cndmask_b32_e32 v209, v170, v209, vcc
	v_sub_f32_e32 v170, v170, v209
	v_exp_f32_e32 v170, v170
	s_nop 0
	v_mul_f32_e32 v167, v167, v170
	v_pk_mul_f32 v[64:65], v[64:65], v[170:171] op_sel_hi:[1,0]
	v_pk_mul_f32 v[62:63], v[62:63], v[170:171] op_sel_hi:[1,0]
	v_pk_mul_f32 v[60:61], v[60:61], v[170:171] op_sel_hi:[1,0]
	v_pk_mul_f32 v[58:59], v[58:59], v[170:171] op_sel_hi:[1,0]
	v_pk_mul_f32 v[56:57], v[56:57], v[170:171] op_sel_hi:[1,0]
	v_pk_mul_f32 v[54:55], v[54:55], v[170:171] op_sel_hi:[1,0]
	v_pk_mul_f32 v[52:53], v[52:53], v[170:171] op_sel_hi:[1,0]
	v_pk_mul_f32 v[50:51], v[50:51], v[170:171] op_sel_hi:[1,0]
	v_pk_mul_f32 v[48:49], v[48:49], v[170:171] op_sel_hi:[1,0]
	v_pk_mul_f32 v[46:47], v[46:47], v[170:171] op_sel_hi:[1,0]
	v_pk_mul_f32 v[44:45], v[44:45], v[170:171] op_sel_hi:[1,0]
	v_pk_mul_f32 v[42:43], v[42:43], v[170:171] op_sel_hi:[1,0]
	v_pk_mul_f32 v[40:41], v[40:41], v[170:171] op_sel_hi:[1,0]
	v_pk_mul_f32 v[38:39], v[38:39], v[170:171] op_sel_hi:[1,0]
	v_pk_mul_f32 v[36:37], v[36:37], v[170:171] op_sel_hi:[1,0]
	v_pk_mul_f32 v[34:35], v[34:35], v[170:171] op_sel_hi:[1,0]
	v_pk_mul_f32 v[32:33], v[32:33], v[170:171] op_sel_hi:[1,0]
	v_pk_mul_f32 v[30:31], v[30:31], v[170:171] op_sel_hi:[1,0]
	v_pk_mul_f32 v[28:29], v[28:29], v[170:171] op_sel_hi:[1,0]
	v_pk_mul_f32 v[26:27], v[26:27], v[170:171] op_sel_hi:[1,0]
	v_pk_mul_f32 v[24:25], v[24:25], v[170:171] op_sel_hi:[1,0]
	v_pk_mul_f32 v[22:23], v[22:23], v[170:171] op_sel_hi:[1,0]
	v_pk_mul_f32 v[20:21], v[20:21], v[170:171] op_sel_hi:[1,0]
	v_pk_mul_f32 v[18:19], v[18:19], v[170:171] op_sel_hi:[1,0]
	v_pk_mul_f32 v[16:17], v[16:17], v[170:171] op_sel_hi:[1,0]
	v_pk_mul_f32 v[14:15], v[14:15], v[170:171] op_sel_hi:[1,0]
	v_pk_mul_f32 v[12:13], v[12:13], v[170:171] op_sel_hi:[1,0]
	v_pk_mul_f32 v[10:11], v[10:11], v[170:171] op_sel_hi:[1,0]
	v_pk_mul_f32 v[8:9], v[8:9], v[170:171] op_sel_hi:[1,0]
	v_pk_mul_f32 v[6:7], v[6:7], v[170:171] op_sel_hi:[1,0]
	v_pk_mul_f32 v[4:5], v[4:5], v[170:171] op_sel_hi:[1,0]
	v_pk_mul_f32 v[2:3], v[2:3], v[170:171] op_sel_hi:[1,0]
	v_mov_b32_e32 v170, v209

; #define ATT_VREAD(dst, q_) do { const LAS char* vp_ = (const LAS char*)vb + (((q_) >> 1) * 32 + 16 * ((q_) & 1)) * VSTR; \
;         _Pragma("unroll") for (int d_ = 0; d_ < 4; ++d_) { dst[d_][0] = vtr(vp_ + voff[d_][0]); dst[d_][1] = vtr(vp_ + 8 * VSTR + voff[d_][1]); } } while (0)
;     ...
;         float mx = fmaxf(s0[0], s1[0]);
; #pragma unroll
;         for (int r = 1; r < 16; ++r) mx = fmaxf(mx, fmaxf(s0[r], s1[r]));
;         mx = fmaxf(mx, __shfl_xor(mx, 32));
;         const bool need = mx > mrun + 8.f;
;         if (__any(need)) { const float mnew = need ? mx : mrun, alpha = __builtin_amdgcn_exp2f(mrun - mnew); mrun = mnew; lrun *= alpha;
; #pragma unroll
;             for (int d = 0; d < 4; ++d)
; #pragma unroll
;                 for (int r = 0; r < 16; ++r) o[d][r] *= alpha; }
;     ...
;             if (wkb) { vb = sbb + KBUF + vlane; ATT_VREAD(vpre, 0); SM(wb0, wb1, b0, b1, pbb);
.LBB0_3324:
	s_and_b64 vcc, exec, s[2:3]
	s_cbranch_vccnz .LBB0_3328
	v_max3_f32 v154, v115, v83, v116
	v_max3_f32 v155, v122, v90, v123
	v_max3_f32 v154, v154, v84, v117
	v_max3_f32 v155, v155, v91, v124
	v_max3_f32 v154, v154, v85, v82
	v_max3_f32 v155, v155, v92, v125
	v_max3_f32 v154, v154, v114, v118
	v_max3_f32 v155, v155, v93, v126
	v_max3_f32 v154, v154, v86, v119
	v_max3_f32 v155, v155, v94, v127
	v_max3_f32 v154, v154, v87, v120
	v_max3_f32 v155, v155, v95, v128
	v_max3_f32 v154, v154, v88, v121
	v_max3_f32 v155, v155, v96, v129
	v_max3_f32 v154, v154, v155, v89
	v_max_f32_e32 v209, v97, v154
	s_waitcnt vmcnt(0)
	ds_read_b64_tr_b16 v[150:151], v201 offset:49152
	ds_read_b64_tr_b16 v[152:153], v202 offset:51200
	ds_read_b64_tr_b16 v[146:147], v203 offset:49152
	ds_read_b64_tr_b16 v[148:149], v204 offset:51200
	v_mov_b32_e32 v246, v209
	v_mov_b32_e32 v247, v209
	ds_read_b64_tr_b16 v[158:159], v205 offset:49152
	ds_read_b64_tr_b16 v[160:161], v206 offset:51200
	ds_read_b64_tr_b16 v[154:155], v207 offset:49152
	ds_read_b64_tr_b16 v[156:157], v208 offset:51200
	v_permlane32_swap_b32_e32 v246, v247
	v_max3_f32 v209, v209, v246, v247
	v_add_f32_e32 v210, 0x41000000, v170
	v_cmp_gt_f32_e32 vcc, v209, v210
	s_cbranch_vccz .LBB0_3327
	s_nop 0
	v_cndmask_b32_e32 v209, v170, v209, vcc
	v_sub_f32_e32 v170, v170, v209
	v_exp_f32_e32 v170, v170
	s_nop 0
	v_mul_f32_e32 v167, v167, v170
	v_pk_mul_f32 v[64:65], v[64:65], v[170:171] op_sel_hi:[1,0]
	v_pk_mul_f32 v[62:63], v[62:63], v[170:171] op_sel_hi:[1,0]
	v_pk_mul_f32 v[60:61], v[60:61], v[170:171] op_sel_hi:[1,0]
	v_pk_mul_f32 v[58:59], v[58:59], v[170:171] op_sel_hi:[1,0]
	v_pk_mul_f32 v[56:57], v[56:57], v[170:171] op_sel_hi:[1,0]
	v_pk_mul_f32 v[54:55], v[54:55], v[170:171] op_sel_hi:[1,0]
	v_pk_mul_f32 v[52:53], v[52:53], v[170:171] op_sel_hi:[1,0]
	v_pk_mul_f32 v[50:51], v[50:51], v[170:171] op_sel_hi:[1,0]
	v_pk_mul_f32 v[48:49], v[48:49], v[170:171] op_sel_hi:[1,0]
	v_pk_mul_f32 v[46:47], v[46:47], v[170:171] op_sel_hi:[1,0]
	v_pk_mul_f32 v[44:45], v[44:45], v[170:171] op_sel_hi:[1,0]
	v_pk_mul_f32 v[42:43], v[42:43], v[170:171] op_sel_hi:[1,0]
	v_pk_mul_f32 v[40:41], v[40:41], v[170:171] op_sel_hi:[1,0]
	v_pk_mul_f32 v[38:39], v[38:39], v[170:171] op_sel_hi:[1,0]
	v_pk_mul_f32 v[36:37], v[36:37], v[170:171] op_sel_hi:[1,0]
	v_pk_mul_f32 v[34:35], v[34:35], v[170:171] op_sel_hi:[1,0]
	v_pk_mul_f32 v[32:33], v[32:33], v[170:171] op_sel_hi:[1,0]
	v_pk_mul_f32 v[30:31], v[30:31], v[170:171] op_sel_hi:[1,0]
	v_pk_mul_f32 v[28:29], v[28:29], v[170:171] op_sel_hi:[1,0]
	v_pk_mul_f32 v[26:27], v[26:27], v[170:171] op_sel_hi:[1,0]
	v_pk_mul_f32 v[24:25], v[24:25], v[170:171] op_sel_hi:[1,0]
	v_pk_mul_f32 v[22:23], v[22:23], v[170:171] op_sel_hi:[1,0]
	v_pk_mul_f32 v[20:21], v[20:21], v[170:171] op_sel_hi:[1,0]
	v_pk_mul_f32 v[18:19], v[18:19], v[170:171] op_sel_hi:[1,0]
	v_pk_mul_f32 v[16:17], v[16:17], v[170:171] op_sel_hi:[1,0]
	v_pk_mul_f32 v[14:15], v[14:15], v[170:171] op_sel_hi:[1,0]
	v_pk_mul_f32 v[12:13], v[12:13], v[170:171] op_sel_hi:[1,0]
	v_pk_mul_f32 v[10:11], v[10:11], v[170:171] op_sel_hi:[1,0]
	v_pk_mul_f32 v[8:9], v[8:9], v[170:171] op_sel_hi:[1,0]
	v_pk_mul_f32 v[6:7], v[6:7], v[170:171] op_sel_hi:[1,0]
	v_pk_mul_f32 v[4:5], v[4:5], v[170:171] op_sel_hi:[1,0]
	v_pk_mul_f32 v[2:3], v[2:3], v[170:171] op_sel_hi:[1,0]
	v_mov_b32_e32 v170, v209
